# 16x16x32 attention (threshold 8) with the B operand kept stationary: Q fragment for 4 MFMAs in K.Q^T, P fragment for 8 MFMAs in P.V
# speedup vs baseline: 1.0092x; 1.0092x over previous
.Latt16_dec:
	s_and_b32 s4, s2, 63
	s_lshr_b32 s5, s2, 6
	s_cmp_ge_u32 s5, 6
	s_cselect_b32 s6, 1, 0
	s_mul_i32 s7, s6, 6
	s_sub_u32 s7, s5, s7
	s_mul_i32 s8, s6, 0x2100
	s_lshl_b32 s9, s4, 7
	s_add_u32 s8, s8, s9
	s_lshl_b32 s9, s11, 5
	s_add_u32 s8, s8, s9
	s_add_u32 s8, s8, 0x100
	s_mul_i32 s8, s8, 0x600
	s_lshl_b32 s9, s7, 8
	s_lshl_b32 s10, s3, 7
	s_add_u32 s12, s9, s10
	s_add_u32 s13, s8, s12
	s_add_u32 s52, s94, s13
	s_addc_u32 s53, s95, 0
	s_add_u32 s52, s52, 0x4510000
	s_addc_u32 s53, s53, 0
	s_mul_i32 s13, s3, 0x18c0000
	s_add_u32 s13, s13, s8
	s_add_u32 s13, s13, s9
	s_add_u32 s50, s94, s13
	s_addc_u32 s51, s95, 0
	s_add_u32 s50, s50, 0x9fd0000
	s_addc_u32 s51, s51, 0
	s_mul_i32 s13, s6, 0xc60000
	s_add_u32 s13, s13, s12
	s_add_u32 s42, s94, s13
	s_addc_u32 s43, s95, 0
	s_add_u32 s42, s42, 0x5dd0000
	s_addc_u32 s43, s43, 0
	s_mul_i32 s13, s6, 0x300
	s_lshl_b32 s9, s7, 7
	s_add_u32 s13, s13, s9
	s_mul_i32 s13, s13, 0x4200
	s_add_u32 s44, s94, s13
	s_addc_u32 s45, s95, 0
	s_add_u32 s44, s44, 0x7690000
	s_addc_u32 s45, s45, 0
	global_load_dwordx4 v[100:103], v224, s[52:53]
	global_load_dwordx4 v[104:107], v224, s[52:53] offset:64
	global_load_dwordx4 v[108:111], v225, s[52:53]
	global_load_dwordx4 v[112:115], v225, s[52:53] offset:64
	s_barrier
	s_mov_b32 m0, s46
	s_nop 0
	global_load_lds_dwordx4 v216, s[42:43]
	s_add_u32 m0, s46, 0x400
	s_nop 0
	global_load_lds_dwordx4 v217, s[42:43]
	s_mov_b32 m0, s47
	s_nop 0
	global_load_lds_dwordx4 v218, s[44:45]
	s_add_u32 m0, s47, 0x400
	s_nop 0
	global_load_lds_dwordx4 v219, s[44:45]
	s_add_u32 m0, s47, 0x800
	s_nop 0
	global_load_lds_dwordx4 v220, s[44:45]
	s_add_u32 m0, s47, 0xc00
	s_nop 0
	global_load_lds_dwordx4 v221, s[44:45]
	s_add_u32 s42, s42, 0x18000
	s_addc_u32 s43, s43, 0
	s_add_u32 s44, s44, 0x80
	s_addc_u32 s45, s45, 0
	v_mov_b32_e32 v4, 0
	v_mov_b32_e32 v5, 0
	v_mov_b32_e32 v6, 0
	v_mov_b32_e32 v7, 0
	v_mov_b32_e32 v8, 0
	v_mov_b32_e32 v9, 0
	v_mov_b32_e32 v10, 0
	v_mov_b32_e32 v11, 0
	v_mov_b32_e32 v12, 0
	v_mov_b32_e32 v13, 0
	v_mov_b32_e32 v14, 0
	v_mov_b32_e32 v15, 0
	v_mov_b32_e32 v16, 0
	v_mov_b32_e32 v17, 0
	v_mov_b32_e32 v18, 0
	v_mov_b32_e32 v19, 0
	v_mov_b32_e32 v20, 0
	v_mov_b32_e32 v21, 0
	v_mov_b32_e32 v22, 0
	v_mov_b32_e32 v23, 0
	v_mov_b32_e32 v24, 0
	v_mov_b32_e32 v25, 0
	v_mov_b32_e32 v26, 0
	v_mov_b32_e32 v27, 0
	v_mov_b32_e32 v28, 0
	v_mov_b32_e32 v29, 0
	v_mov_b32_e32 v30, 0
	v_mov_b32_e32 v31, 0
	v_mov_b32_e32 v32, 0
	v_mov_b32_e32 v33, 0
	v_mov_b32_e32 v34, 0
	v_mov_b32_e32 v35, 0
	v_mov_b32_e32 v36, 0
	v_mov_b32_e32 v37, 0
	v_mov_b32_e32 v38, 0
	v_mov_b32_e32 v39, 0
	v_mov_b32_e32 v40, 0
	v_mov_b32_e32 v41, 0
	v_mov_b32_e32 v42, 0
	v_mov_b32_e32 v43, 0
	v_mov_b32_e32 v44, 0
	v_mov_b32_e32 v45, 0
	v_mov_b32_e32 v46, 0
	v_mov_b32_e32 v47, 0
	v_mov_b32_e32 v48, 0
	v_mov_b32_e32 v49, 0
	v_mov_b32_e32 v50, 0
	v_mov_b32_e32 v51, 0
	v_mov_b32_e32 v52, 0
	v_mov_b32_e32 v53, 0
	v_mov_b32_e32 v54, 0
	v_mov_b32_e32 v55, 0
	v_mov_b32_e32 v56, 0
	v_mov_b32_e32 v57, 0
	v_mov_b32_e32 v58, 0
	v_mov_b32_e32 v59, 0
	v_mov_b32_e32 v60, 0
	v_mov_b32_e32 v61, 0
	v_mov_b32_e32 v62, 0
	v_mov_b32_e32 v63, 0
	v_mov_b32_e32 v64, 0
	v_mov_b32_e32 v65, 0
	v_mov_b32_e32 v66, 0
	v_mov_b32_e32 v67, 0
	v_mov_b32_e32 v116, 0
	v_mov_b32_e32 v117, 0
	v_mov_b32_e32 v118, 0
	v_mov_b32_e32 v119, 0
	v_mov_b32_e32 v120, 0
	v_mov_b32_e32 v121, 0
	v_mov_b32_e32 v122, 0
	v_mov_b32_e32 v123, 0
	v_mov_b32_e32 v126, 0
	v_mov_b32_e32 v127, 0
	s_waitcnt vmcnt(0)
	s_barrier
	ds_read_b128 v[148:151], v222 offset:0
	ds_read_b128 v[152:155], v222 offset:2048
	s_add_u32 m0, s46, 0x6000
	ds_read_b128 v[156:159], v222 offset:4096
	global_load_lds_dwordx4 v216, s[42:43]
	s_add_u32 m0, s46, 0x6400
	ds_read_b128 v[160:163], v222 offset:6144
	global_load_lds_dwordx4 v217, s[42:43]
	s_add_u32 m0, s47, 0x6000
	ds_read_b128 v[164:167], v223 offset:0
	global_load_lds_dwordx4 v218, s[44:45]
	s_add_u32 m0, s47, 0x6400
	ds_read_b128 v[168:171], v223 offset:2048
	global_load_lds_dwordx4 v219, s[44:45]
	s_add_u32 m0, s47, 0x6800
	ds_read_b128 v[172:175], v223 offset:4096
	global_load_lds_dwordx4 v220, s[44:45]
	s_add_u32 m0, s47, 0x6c00
	ds_read_b128 v[176:179], v223 offset:6144
	global_load_lds_dwordx4 v221, s[44:45]
	s_add_u32 s42, s42, 0x18000
	s_addc_u32 s43, s43, 0
	s_add_u32 s44, s44, 0x80
	s_addc_u32 s45, s45, 0
	ds_read_b128 v[180:183], v222 offset:8192
	ds_read_b128 v[184:187], v222 offset:10240
	ds_read_b128 v[188:191], v222 offset:12288
	ds_read_b128 v[192:195], v222 offset:14336
	s_waitcnt lgkmcnt(11)
	v_mfma_f32_16x16x32_bf16 v[68:71], v[148:151], v[100:103], v[116:119]
	s_waitcnt lgkmcnt(10)
	v_mfma_f32_16x16x32_bf16 v[72:75], v[152:155], v[100:103], v[116:119]
	s_waitcnt lgkmcnt(9)
	v_mfma_f32_16x16x32_bf16 v[84:87], v[156:159], v[100:103], v[116:119]
	s_waitcnt lgkmcnt(8)
	v_mfma_f32_16x16x32_bf16 v[88:91], v[160:163], v[100:103], v[116:119]
	v_mfma_f32_16x16x32_bf16 v[76:79], v[148:151], v[108:111], v[120:123]
	ds_read_b128 v[148:151], v222 offset:16384
	v_mfma_f32_16x16x32_bf16 v[80:83], v[152:155], v[108:111], v[120:123]
	ds_read_b128 v[152:155], v222 offset:18432
	v_mfma_f32_16x16x32_bf16 v[92:95], v[156:159], v[108:111], v[120:123]
	ds_read_b128 v[156:159], v222 offset:20480
	v_mfma_f32_16x16x32_bf16 v[96:99], v[160:163], v[108:111], v[120:123]
	ds_read_b128 v[160:163], v222 offset:22528
	s_waitcnt lgkmcnt(11)
	v_mfma_f32_16x16x32_bf16 v[68:71], v[164:167], v[104:107], v[68:71]
	s_waitcnt lgkmcnt(10)
	v_mfma_f32_16x16x32_bf16 v[72:75], v[168:171], v[104:107], v[72:75]
	s_waitcnt lgkmcnt(9)
	v_mfma_f32_16x16x32_bf16 v[84:87], v[172:175], v[104:107], v[84:87]
	s_waitcnt lgkmcnt(8)
	v_mfma_f32_16x16x32_bf16 v[88:91], v[176:179], v[104:107], v[88:91]
	v_mfma_f32_16x16x32_bf16 v[76:79], v[164:167], v[112:115], v[76:79]
	ds_read_b128 v[164:167], v223 offset:8192
	v_mfma_f32_16x16x32_bf16 v[80:83], v[168:171], v[112:115], v[80:83]
	ds_read_b128 v[168:171], v223 offset:10240
	v_mfma_f32_16x16x32_bf16 v[92:95], v[172:175], v[112:115], v[92:95]
	ds_read_b128 v[172:175], v223 offset:12288
	v_mfma_f32_16x16x32_bf16 v[96:99], v[176:179], v[112:115], v[96:99]
	ds_read_b128 v[176:179], v223 offset:14336
	s_nop 7
	v_max3_f32 v200, v68, v69, v70
	v_max3_f32 v201, v71, v72, v73
	v_max3_f32 v202, v74, v75, v84
	v_max3_f32 v203, v85, v86, v87
	v_max3_f32 v204, v88, v89, v90
	v_max3_f32 v200, v200, v201, v91
	v_max3_f32 v202, v202, v203, v204
	v_max_f32_e32 v196, v200, v202
	v_max3_f32 v205, v76, v77, v78
	v_max3_f32 v206, v79, v80, v81
	v_max3_f32 v207, v82, v83, v92
	v_max3_f32 v208, v93, v94, v95
	v_max3_f32 v209, v96, v97, v98
	v_max3_f32 v205, v205, v206, v99
	v_max3_f32 v207, v207, v208, v209
	v_max_f32_e32 v197, v205, v207
	v_max_f32_e32 v198, v196, v197
	ds_bpermute_b32 v199, v226, v196
	s_waitcnt lgkmcnt(0)
	v_max_f32_e32 v196, v196, v199
	ds_bpermute_b32 v199, v227, v196
	s_waitcnt lgkmcnt(0)
	v_max_f32_e32 v196, v196, v199
	ds_bpermute_b32 v199, v226, v197
	s_waitcnt lgkmcnt(0)
	v_max_f32_e32 v197, v197, v199
	ds_bpermute_b32 v199, v227, v197
	s_waitcnt lgkmcnt(0)
	v_max_f32_e32 v197, v197, v199
	v_sub_f32_e32 v68, v68, v196
	v_sub_f32_e32 v69, v69, v196
	v_sub_f32_e32 v70, v70, v196
	v_sub_f32_e32 v71, v71, v196
	v_sub_f32_e32 v72, v72, v196
	v_sub_f32_e32 v73, v73, v196
	v_sub_f32_e32 v74, v74, v196
	v_sub_f32_e32 v75, v75, v196
	v_sub_f32_e32 v84, v84, v196
	v_sub_f32_e32 v85, v85, v196
	v_sub_f32_e32 v86, v86, v196
	v_sub_f32_e32 v87, v87, v196
	v_sub_f32_e32 v88, v88, v196
	v_sub_f32_e32 v89, v89, v196
	v_sub_f32_e32 v90, v90, v196
	v_sub_f32_e32 v91, v91, v196
	v_mov_b32_e32 v124, v196
	v_sub_f32_e32 v116, 0, v124
	v_mov_b32_e32 v117, v116
	v_mov_b32_e32 v118, v116
	v_mov_b32_e32 v119, v116
	v_sub_f32_e32 v76, v76, v197
	v_sub_f32_e32 v77, v77, v197
	v_sub_f32_e32 v78, v78, v197
	v_sub_f32_e32 v79, v79, v197
	v_sub_f32_e32 v80, v80, v197
	v_sub_f32_e32 v81, v81, v197
	v_sub_f32_e32 v82, v82, v197
	v_sub_f32_e32 v83, v83, v197
	v_sub_f32_e32 v92, v92, v197
	v_sub_f32_e32 v93, v93, v197
	v_sub_f32_e32 v94, v94, v197
	v_sub_f32_e32 v95, v95, v197
	v_sub_f32_e32 v96, v96, v197
	v_sub_f32_e32 v97, v97, v197
	v_sub_f32_e32 v98, v98, v197
	v_sub_f32_e32 v99, v99, v197
	v_mov_b32_e32 v125, v197
	v_sub_f32_e32 v120, 0, v125
	v_mov_b32_e32 v121, v120
	v_mov_b32_e32 v122, v120
	v_mov_b32_e32 v123, v120
	v_exp_f32_e32 v68, v68
	v_exp_f32_e32 v69, v69
	v_exp_f32_e32 v70, v70
	v_exp_f32_e32 v71, v71
	v_exp_f32_e32 v72, v72
	v_exp_f32_e32 v73, v73
	v_exp_f32_e32 v74, v74
	v_exp_f32_e32 v75, v75
	v_add_f32_e32 v228, v68, v69
	v_add_f32_e32 v228, v228, v70
	v_add_f32_e32 v228, v228, v71
	v_add_f32_e32 v228, v228, v72
	v_add_f32_e32 v228, v228, v73
	v_add_f32_e32 v228, v228, v74
	v_add_f32_e32 v228, v228, v75
	v_cvt_pk_bf16_f32 v68, v68, v69
	v_cvt_pk_bf16_f32 v69, v70, v71
	v_cvt_pk_bf16_f32 v70, v72, v73
	v_cvt_pk_bf16_f32 v71, v74, v75
	v_exp_f32_e32 v76, v76
	v_exp_f32_e32 v77, v77
	v_exp_f32_e32 v78, v78
	v_exp_f32_e32 v79, v79
	v_exp_f32_e32 v80, v80
	v_exp_f32_e32 v81, v81
	v_exp_f32_e32 v82, v82
	v_exp_f32_e32 v83, v83
	v_add_f32_e32 v229, v76, v77
	v_add_f32_e32 v229, v229, v78
	v_add_f32_e32 v229, v229, v79
	v_add_f32_e32 v229, v229, v80
	v_add_f32_e32 v229, v229, v81
	v_add_f32_e32 v229, v229, v82
	v_add_f32_e32 v229, v229, v83
	v_cvt_pk_bf16_f32 v76, v76, v77
	v_cvt_pk_bf16_f32 v77, v78, v79
	v_cvt_pk_bf16_f32 v78, v80, v81
	v_cvt_pk_bf16_f32 v79, v82, v83
	v_exp_f32_e32 v84, v84
	v_exp_f32_e32 v85, v85
	s_waitcnt lgkmcnt(11)
	v_mfma_f32_16x16x32_bf16 v[4:7], v[180:183], v[68:71], v[4:7]
	v_exp_f32_e32 v86, v86
	v_exp_f32_e32 v87, v87
	s_waitcnt lgkmcnt(10)
	v_mfma_f32_16x16x32_bf16 v[12:15], v[184:187], v[68:71], v[12:15]
	v_exp_f32_e32 v88, v88
	v_exp_f32_e32 v89, v89
	s_waitcnt lgkmcnt(9)
	v_mfma_f32_16x16x32_bf16 v[20:23], v[188:191], v[68:71], v[20:23]
	v_exp_f32_e32 v90, v90
	v_exp_f32_e32 v91, v91
	s_waitcnt lgkmcnt(8)
	v_mfma_f32_16x16x32_bf16 v[28:31], v[192:195], v[68:71], v[28:31]
	v_add_f32_e32 v228, v228, v84
	v_add_f32_e32 v228, v228, v85
	v_add_f32_e32 v228, v228, v86
	v_add_f32_e32 v228, v228, v87
	s_waitcnt lgkmcnt(7)
	v_mfma_f32_16x16x32_bf16 v[36:39], v[148:151], v[68:71], v[36:39]
	v_add_f32_e32 v228, v228, v88
	v_add_f32_e32 v228, v228, v89
	v_add_f32_e32 v228, v228, v90
	v_add_f32_e32 v228, v228, v91
	s_waitcnt lgkmcnt(6)
	v_mfma_f32_16x16x32_bf16 v[44:47], v[152:155], v[68:71], v[44:47]
	v_cvt_pk_bf16_f32 v84, v84, v85
	v_cvt_pk_bf16_f32 v85, v86, v87
	v_cvt_pk_bf16_f32 v86, v88, v89
	v_cvt_pk_bf16_f32 v87, v90, v91
	s_waitcnt lgkmcnt(5)
	v_mfma_f32_16x16x32_bf16 v[52:55], v[156:159], v[68:71], v[52:55]
	v_exp_f32_e32 v92, v92
	v_exp_f32_e32 v93, v93
	s_waitcnt lgkmcnt(4)
	v_mfma_f32_16x16x32_bf16 v[60:63], v[160:163], v[68:71], v[60:63]
	v_exp_f32_e32 v94, v94
	v_exp_f32_e32 v95, v95
	v_mfma_f32_16x16x32_bf16 v[8:11], v[180:183], v[76:79], v[8:11]
	v_exp_f32_e32 v96, v96
	v_exp_f32_e32 v97, v97
	ds_read_b128 v[180:183], v223 offset:16384
	v_mfma_f32_16x16x32_bf16 v[16:19], v[184:187], v[76:79], v[16:19]
	v_exp_f32_e32 v98, v98
	v_exp_f32_e32 v99, v99
	ds_read_b128 v[184:187], v223 offset:18432
	v_mfma_f32_16x16x32_bf16 v[24:27], v[188:191], v[76:79], v[24:27]
	v_add_f32_e32 v229, v229, v92
	v_add_f32_e32 v229, v229, v93
	v_add_f32_e32 v229, v229, v94
	v_add_f32_e32 v229, v229, v95
	ds_read_b128 v[188:191], v223 offset:20480
	v_mfma_f32_16x16x32_bf16 v[32:35], v[192:195], v[76:79], v[32:35]
	v_add_f32_e32 v229, v229, v96
	v_add_f32_e32 v229, v229, v97
	v_add_f32_e32 v229, v229, v98
	v_add_f32_e32 v229, v229, v99
	ds_read_b128 v[192:195], v223 offset:22528
	v_mfma_f32_16x16x32_bf16 v[40:43], v[148:151], v[76:79], v[40:43]
	v_cvt_pk_bf16_f32 v92, v92, v93
	v_cvt_pk_bf16_f32 v93, v94, v95
	v_cvt_pk_bf16_f32 v94, v96, v97
	v_cvt_pk_bf16_f32 v95, v98, v99
	v_mfma_f32_16x16x32_bf16 v[48:51], v[152:155], v[76:79], v[48:51]
	v_mfma_f32_16x16x32_bf16 v[56:59], v[156:159], v[76:79], v[56:59]
	v_mfma_f32_16x16x32_bf16 v[64:67], v[160:163], v[76:79], v[64:67]
	s_nop 1
	s_waitcnt lgkmcnt(7)
	v_mfma_f32_16x16x32_bf16 v[4:7], v[164:167], v[84:87], v[4:7]
	s_waitcnt lgkmcnt(6)
	v_mfma_f32_16x16x32_bf16 v[12:15], v[168:171], v[84:87], v[12:15]
	s_waitcnt lgkmcnt(5)
	v_mfma_f32_16x16x32_bf16 v[20:23], v[172:175], v[84:87], v[20:23]
	s_waitcnt lgkmcnt(4)
	v_mfma_f32_16x16x32_bf16 v[28:31], v[176:179], v[84:87], v[28:31]
	s_waitcnt lgkmcnt(3)
	v_mfma_f32_16x16x32_bf16 v[36:39], v[180:183], v[84:87], v[36:39]
	s_waitcnt lgkmcnt(2)
	v_mfma_f32_16x16x32_bf16 v[44:47], v[184:187], v[84:87], v[44:47]
	s_waitcnt lgkmcnt(1)
	v_mfma_f32_16x16x32_bf16 v[52:55], v[188:191], v[84:87], v[52:55]
	s_waitcnt lgkmcnt(0)
	v_mfma_f32_16x16x32_bf16 v[60:63], v[192:195], v[84:87], v[60:63]
	v_mfma_f32_16x16x32_bf16 v[8:11], v[164:167], v[92:95], v[8:11]
	v_mfma_f32_16x16x32_bf16 v[16:19], v[168:171], v[92:95], v[16:19]
	v_mfma_f32_16x16x32_bf16 v[24:27], v[172:175], v[92:95], v[24:27]
	v_mfma_f32_16x16x32_bf16 v[32:35], v[176:179], v[92:95], v[32:35]
	v_mfma_f32_16x16x32_bf16 v[40:43], v[180:183], v[92:95], v[40:43]
	v_mfma_f32_16x16x32_bf16 v[48:51], v[184:187], v[92:95], v[48:51]
	v_mfma_f32_16x16x32_bf16 v[56:59], v[188:191], v[92:95], v[56:59]
	v_mfma_f32_16x16x32_bf16 v[64:67], v[192:195], v[92:95], v[64:67]
	v_add_f32_e32 v126, v126, v228
	v_add_f32_e32 v127, v127, v229
	s_movk_i32 s48, 0x41
.Latt16_loop:
	s_waitcnt vmcnt(0)
	s_barrier
	ds_read_b128 v[148:151], v222 offset:24576
	ds_read_b128 v[152:155], v222 offset:26624
	s_mov_b32 m0, s46
	ds_read_b128 v[156:159], v222 offset:28672
	global_load_lds_dwordx4 v216, s[42:43]
	s_add_u32 m0, s46, 0x400
	ds_read_b128 v[160:163], v222 offset:30720
	global_load_lds_dwordx4 v217, s[42:43]
	s_mov_b32 m0, s47
	ds_read_b128 v[164:167], v223 offset:24576
	global_load_lds_dwordx4 v218, s[44:45]
	s_add_u32 m0, s47, 0x400
	ds_read_b128 v[168:171], v223 offset:26624
	global_load_lds_dwordx4 v219, s[44:45]
	s_add_u32 m0, s47, 0x800
	ds_read_b128 v[172:175], v223 offset:28672
	global_load_lds_dwordx4 v220, s[44:45]
	s_add_u32 m0, s47, 0xc00
	ds_read_b128 v[176:179], v223 offset:30720
	global_load_lds_dwordx4 v221, s[44:45]
	s_add_u32 s42, s42, 0x18000
	s_addc_u32 s43, s43, 0
	s_add_u32 s44, s44, 0x80
	s_addc_u32 s45, s45, 0
	ds_read_b128 v[180:183], v222 offset:32768
	ds_read_b128 v[184:187], v222 offset:34816
	ds_read_b128 v[188:191], v222 offset:36864
	ds_read_b128 v[192:195], v222 offset:38912
	s_waitcnt lgkmcnt(11)
	v_mfma_f32_16x16x32_bf16 v[68:71], v[148:151], v[100:103], v[116:119]
	s_waitcnt lgkmcnt(10)
	v_mfma_f32_16x16x32_bf16 v[72:75], v[152:155], v[100:103], v[116:119]
	s_waitcnt lgkmcnt(9)
	v_mfma_f32_16x16x32_bf16 v[84:87], v[156:159], v[100:103], v[116:119]
	s_waitcnt lgkmcnt(8)
	v_mfma_f32_16x16x32_bf16 v[88:91], v[160:163], v[100:103], v[116:119]
	v_mfma_f32_16x16x32_bf16 v[76:79], v[148:151], v[108:111], v[120:123]
	ds_read_b128 v[148:151], v222 offset:40960
	v_mfma_f32_16x16x32_bf16 v[80:83], v[152:155], v[108:111], v[120:123]
	ds_read_b128 v[152:155], v222 offset:43008
	v_mfma_f32_16x16x32_bf16 v[92:95], v[156:159], v[108:111], v[120:123]
	ds_read_b128 v[156:159], v222 offset:45056
	v_mfma_f32_16x16x32_bf16 v[96:99], v[160:163], v[108:111], v[120:123]
	ds_read_b128 v[160:163], v222 offset:47104
	s_waitcnt lgkmcnt(11)
	v_mfma_f32_16x16x32_bf16 v[68:71], v[164:167], v[104:107], v[68:71]
	s_waitcnt lgkmcnt(10)
	v_mfma_f32_16x16x32_bf16 v[72:75], v[168:171], v[104:107], v[72:75]
	s_waitcnt lgkmcnt(9)
	v_mfma_f32_16x16x32_bf16 v[84:87], v[172:175], v[104:107], v[84:87]
	s_waitcnt lgkmcnt(8)
	v_mfma_f32_16x16x32_bf16 v[88:91], v[176:179], v[104:107], v[88:91]
	v_mfma_f32_16x16x32_bf16 v[76:79], v[164:167], v[112:115], v[76:79]
	ds_read_b128 v[164:167], v223 offset:32768
	v_mfma_f32_16x16x32_bf16 v[80:83], v[168:171], v[112:115], v[80:83]
	ds_read_b128 v[168:171], v223 offset:34816
	v_mfma_f32_16x16x32_bf16 v[92:95], v[172:175], v[112:115], v[92:95]
	ds_read_b128 v[172:175], v223 offset:36864
	v_mfma_f32_16x16x32_bf16 v[96:99], v[176:179], v[112:115], v[96:99]
	ds_read_b128 v[176:179], v223 offset:38912
	s_nop 7
	v_max3_f32 v200, v68, v69, v70
	v_max3_f32 v201, v71, v72, v73
	v_max3_f32 v202, v74, v75, v84
	v_max3_f32 v203, v85, v86, v87
	v_max3_f32 v204, v88, v89, v90
	v_max3_f32 v200, v200, v201, v91
	v_max3_f32 v202, v202, v203, v204
	v_max_f32_e32 v196, v200, v202
	v_max3_f32 v205, v76, v77, v78
	v_max3_f32 v206, v79, v80, v81
	v_max3_f32 v207, v82, v83, v92
	v_max3_f32 v208, v93, v94, v95
	v_max3_f32 v209, v96, v97, v98
	v_max3_f32 v205, v205, v206, v99
	v_max3_f32 v207, v207, v208, v209
	v_max_f32_e32 v197, v205, v207
	v_max_f32_e32 v198, v196, v197
	v_cmp_lt_f32_e32 vcc, 0x41000000, v198
	s_cbranch_vccnz .Latt16_resc_a
.Latt16_cont_a:
	v_exp_f32_e32 v68, v68
	v_exp_f32_e32 v69, v69
	v_exp_f32_e32 v70, v70
	v_exp_f32_e32 v71, v71
	v_exp_f32_e32 v72, v72
	v_exp_f32_e32 v73, v73
	v_exp_f32_e32 v74, v74
	v_exp_f32_e32 v75, v75
	v_add_f32_e32 v228, v68, v69
	v_add_f32_e32 v228, v228, v70
	v_add_f32_e32 v228, v228, v71
	v_add_f32_e32 v228, v228, v72
	v_add_f32_e32 v228, v228, v73
	v_add_f32_e32 v228, v228, v74
	v_add_f32_e32 v228, v228, v75
	v_cvt_pk_bf16_f32 v68, v68, v69
	v_cvt_pk_bf16_f32 v69, v70, v71
	v_cvt_pk_bf16_f32 v70, v72, v73
	v_cvt_pk_bf16_f32 v71, v74, v75
	v_exp_f32_e32 v76, v76
	v_exp_f32_e32 v77, v77
	v_exp_f32_e32 v78, v78
	v_exp_f32_e32 v79, v79
	v_exp_f32_e32 v80, v80
	v_exp_f32_e32 v81, v81
	v_exp_f32_e32 v82, v82
	v_exp_f32_e32 v83, v83
	v_add_f32_e32 v229, v76, v77
	v_add_f32_e32 v229, v229, v78
	v_add_f32_e32 v229, v229, v79
	v_add_f32_e32 v229, v229, v80
	v_add_f32_e32 v229, v229, v81
	v_add_f32_e32 v229, v229, v82
	v_add_f32_e32 v229, v229, v83
	v_cvt_pk_bf16_f32 v76, v76, v77
	v_cvt_pk_bf16_f32 v77, v78, v79
	v_cvt_pk_bf16_f32 v78, v80, v81
	v_cvt_pk_bf16_f32 v79, v82, v83
	v_exp_f32_e32 v84, v84
	v_exp_f32_e32 v85, v85
	s_waitcnt lgkmcnt(11)
	v_mfma_f32_16x16x32_bf16 v[4:7], v[180:183], v[68:71], v[4:7]
	v_exp_f32_e32 v86, v86
	v_exp_f32_e32 v87, v87
	s_waitcnt lgkmcnt(10)
	v_mfma_f32_16x16x32_bf16 v[12:15], v[184:187], v[68:71], v[12:15]
	v_exp_f32_e32 v88, v88
	v_exp_f32_e32 v89, v89
	s_waitcnt lgkmcnt(9)
	v_mfma_f32_16x16x32_bf16 v[20:23], v[188:191], v[68:71], v[20:23]
	v_exp_f32_e32 v90, v90
	v_exp_f32_e32 v91, v91
	s_waitcnt lgkmcnt(8)
	v_mfma_f32_16x16x32_bf16 v[28:31], v[192:195], v[68:71], v[28:31]
	v_add_f32_e32 v228, v228, v84
	v_add_f32_e32 v228, v228, v85
	v_add_f32_e32 v228, v228, v86
	v_add_f32_e32 v228, v228, v87
	s_waitcnt lgkmcnt(7)
	v_mfma_f32_16x16x32_bf16 v[36:39], v[148:151], v[68:71], v[36:39]
	v_add_f32_e32 v228, v228, v88
	v_add_f32_e32 v228, v228, v89
	v_add_f32_e32 v228, v228, v90
	v_add_f32_e32 v228, v228, v91
	s_waitcnt lgkmcnt(6)
	v_mfma_f32_16x16x32_bf16 v[44:47], v[152:155], v[68:71], v[44:47]
	v_cvt_pk_bf16_f32 v84, v84, v85
	v_cvt_pk_bf16_f32 v85, v86, v87
	v_cvt_pk_bf16_f32 v86, v88, v89
	v_cvt_pk_bf16_f32 v87, v90, v91
	s_waitcnt lgkmcnt(5)
	v_mfma_f32_16x16x32_bf16 v[52:55], v[156:159], v[68:71], v[52:55]
	v_exp_f32_e32 v92, v92
	v_exp_f32_e32 v93, v93
	s_waitcnt lgkmcnt(4)
	v_mfma_f32_16x16x32_bf16 v[60:63], v[160:163], v[68:71], v[60:63]
	v_exp_f32_e32 v94, v94
	v_exp_f32_e32 v95, v95
	v_mfma_f32_16x16x32_bf16 v[8:11], v[180:183], v[76:79], v[8:11]
	v_exp_f32_e32 v96, v96
	v_exp_f32_e32 v97, v97
	ds_read_b128 v[180:183], v223 offset:40960
	v_mfma_f32_16x16x32_bf16 v[16:19], v[184:187], v[76:79], v[16:19]
	v_exp_f32_e32 v98, v98
	v_exp_f32_e32 v99, v99
	ds_read_b128 v[184:187], v223 offset:43008
	v_mfma_f32_16x16x32_bf16 v[24:27], v[188:191], v[76:79], v[24:27]
	v_add_f32_e32 v229, v229, v92
	v_add_f32_e32 v229, v229, v93
	v_add_f32_e32 v229, v229, v94
	v_add_f32_e32 v229, v229, v95
	ds_read_b128 v[188:191], v223 offset:45056
	v_mfma_f32_16x16x32_bf16 v[32:35], v[192:195], v[76:79], v[32:35]
	v_add_f32_e32 v229, v229, v96
	v_add_f32_e32 v229, v229, v97
	v_add_f32_e32 v229, v229, v98
	v_add_f32_e32 v229, v229, v99
	ds_read_b128 v[192:195], v223 offset:47104
	v_mfma_f32_16x16x32_bf16 v[40:43], v[148:151], v[76:79], v[40:43]
	v_cvt_pk_bf16_f32 v92, v92, v93
	v_cvt_pk_bf16_f32 v93, v94, v95
	v_cvt_pk_bf16_f32 v94, v96, v97
	v_cvt_pk_bf16_f32 v95, v98, v99
	v_mfma_f32_16x16x32_bf16 v[48:51], v[152:155], v[76:79], v[48:51]
	v_mfma_f32_16x16x32_bf16 v[56:59], v[156:159], v[76:79], v[56:59]
	v_mfma_f32_16x16x32_bf16 v[64:67], v[160:163], v[76:79], v[64:67]
	s_nop 1
	s_waitcnt lgkmcnt(7)
	v_mfma_f32_16x16x32_bf16 v[4:7], v[164:167], v[84:87], v[4:7]
	s_waitcnt lgkmcnt(6)
	v_mfma_f32_16x16x32_bf16 v[12:15], v[168:171], v[84:87], v[12:15]
	s_waitcnt lgkmcnt(5)
	v_mfma_f32_16x16x32_bf16 v[20:23], v[172:175], v[84:87], v[20:23]
	s_waitcnt lgkmcnt(4)
	v_mfma_f32_16x16x32_bf16 v[28:31], v[176:179], v[84:87], v[28:31]
	s_waitcnt lgkmcnt(3)
	v_mfma_f32_16x16x32_bf16 v[36:39], v[180:183], v[84:87], v[36:39]
	s_waitcnt lgkmcnt(2)
	v_mfma_f32_16x16x32_bf16 v[44:47], v[184:187], v[84:87], v[44:47]
	s_waitcnt lgkmcnt(1)
	v_mfma_f32_16x16x32_bf16 v[52:55], v[188:191], v[84:87], v[52:55]
	s_waitcnt lgkmcnt(0)
	v_mfma_f32_16x16x32_bf16 v[60:63], v[192:195], v[84:87], v[60:63]
	v_mfma_f32_16x16x32_bf16 v[8:11], v[164:167], v[92:95], v[8:11]
	v_mfma_f32_16x16x32_bf16 v[16:19], v[168:171], v[92:95], v[16:19]
	v_mfma_f32_16x16x32_bf16 v[24:27], v[172:175], v[92:95], v[24:27]
	v_mfma_f32_16x16x32_bf16 v[32:35], v[176:179], v[92:95], v[32:35]
	v_mfma_f32_16x16x32_bf16 v[40:43], v[180:183], v[92:95], v[40:43]
	v_mfma_f32_16x16x32_bf16 v[48:51], v[184:187], v[92:95], v[48:51]
	v_mfma_f32_16x16x32_bf16 v[56:59], v[188:191], v[92:95], v[56:59]
	v_mfma_f32_16x16x32_bf16 v[64:67], v[192:195], v[92:95], v[64:67]
	v_add_f32_e32 v126, v126, v228
	v_add_f32_e32 v127, v127, v229
	s_waitcnt vmcnt(0)
	s_barrier
	ds_read_b128 v[148:151], v222 offset:0
	ds_read_b128 v[152:155], v222 offset:2048
	s_add_u32 m0, s46, 0x6000
	ds_read_b128 v[156:159], v222 offset:4096
	global_load_lds_dwordx4 v216, s[42:43]
	s_add_u32 m0, s46, 0x6400
	ds_read_b128 v[160:163], v222 offset:6144
	global_load_lds_dwordx4 v217, s[42:43]
	s_add_u32 m0, s47, 0x6000
	ds_read_b128 v[164:167], v223 offset:0
	global_load_lds_dwordx4 v218, s[44:45]
	s_add_u32 m0, s47, 0x6400
	ds_read_b128 v[168:171], v223 offset:2048
	global_load_lds_dwordx4 v219, s[44:45]
	s_add_u32 m0, s47, 0x6800
	ds_read_b128 v[172:175], v223 offset:4096
	global_load_lds_dwordx4 v220, s[44:45]
	s_add_u32 m0, s47, 0x6c00
	ds_read_b128 v[176:179], v223 offset:6144
	global_load_lds_dwordx4 v221, s[44:45]
	s_add_u32 s42, s42, 0x18000
	s_addc_u32 s43, s43, 0
	s_add_u32 s44, s44, 0x80
	s_addc_u32 s45, s45, 0
	ds_read_b128 v[180:183], v222 offset:8192
	ds_read_b128 v[184:187], v222 offset:10240
	ds_read_b128 v[188:191], v222 offset:12288
	ds_read_b128 v[192:195], v222 offset:14336
	s_waitcnt lgkmcnt(11)
	v_mfma_f32_16x16x32_bf16 v[68:71], v[148:151], v[100:103], v[116:119]
	s_waitcnt lgkmcnt(10)
	v_mfma_f32_16x16x32_bf16 v[72:75], v[152:155], v[100:103], v[116:119]
	s_waitcnt lgkmcnt(9)
	v_mfma_f32_16x16x32_bf16 v[84:87], v[156:159], v[100:103], v[116:119]
	s_waitcnt lgkmcnt(8)
	v_mfma_f32_16x16x32_bf16 v[88:91], v[160:163], v[100:103], v[116:119]
	v_mfma_f32_16x16x32_bf16 v[76:79], v[148:151], v[108:111], v[120:123]
	ds_read_b128 v[148:151], v222 offset:16384
	v_mfma_f32_16x16x32_bf16 v[80:83], v[152:155], v[108:111], v[120:123]
	ds_read_b128 v[152:155], v222 offset:18432
	v_mfma_f32_16x16x32_bf16 v[92:95], v[156:159], v[108:111], v[120:123]
	ds_read_b128 v[156:159], v222 offset:20480
	v_mfma_f32_16x16x32_bf16 v[96:99], v[160:163], v[108:111], v[120:123]
	ds_read_b128 v[160:163], v222 offset:22528
	s_waitcnt lgkmcnt(11)
	v_mfma_f32_16x16x32_bf16 v[68:71], v[164:167], v[104:107], v[68:71]
	s_waitcnt lgkmcnt(10)
	v_mfma_f32_16x16x32_bf16 v[72:75], v[168:171], v[104:107], v[72:75]
	s_waitcnt lgkmcnt(9)
	v_mfma_f32_16x16x32_bf16 v[84:87], v[172:175], v[104:107], v[84:87]
	s_waitcnt lgkmcnt(8)
	v_mfma_f32_16x16x32_bf16 v[88:91], v[176:179], v[104:107], v[88:91]
	v_mfma_f32_16x16x32_bf16 v[76:79], v[164:167], v[112:115], v[76:79]
	ds_read_b128 v[164:167], v223 offset:8192
	v_mfma_f32_16x16x32_bf16 v[80:83], v[168:171], v[112:115], v[80:83]
	ds_read_b128 v[168:171], v223 offset:10240
	v_mfma_f32_16x16x32_bf16 v[92:95], v[172:175], v[112:115], v[92:95]
	ds_read_b128 v[172:175], v223 offset:12288
	v_mfma_f32_16x16x32_bf16 v[96:99], v[176:179], v[112:115], v[96:99]
	ds_read_b128 v[176:179], v223 offset:14336
	s_nop 7
	v_max3_f32 v200, v68, v69, v70
	v_max3_f32 v201, v71, v72, v73
	v_max3_f32 v202, v74, v75, v84
	v_max3_f32 v203, v85, v86, v87
	v_max3_f32 v204, v88, v89, v90
	v_max3_f32 v200, v200, v201, v91
	v_max3_f32 v202, v202, v203, v204
	v_max_f32_e32 v196, v200, v202
	v_max3_f32 v205, v76, v77, v78
	v_max3_f32 v206, v79, v80, v81
	v_max3_f32 v207, v82, v83, v92
	v_max3_f32 v208, v93, v94, v95
	v_max3_f32 v209, v96, v97, v98
	v_max3_f32 v205, v205, v206, v99
	v_max3_f32 v207, v207, v208, v209
	v_max_f32_e32 v197, v205, v207
	v_max_f32_e32 v198, v196, v197
	v_cmp_lt_f32_e32 vcc, 0x41000000, v198
	s_cbranch_vccnz .Latt16_resc_b
.Latt16_cont_b:
	v_exp_f32_e32 v68, v68
	v_exp_f32_e32 v69, v69
	v_exp_f32_e32 v70, v70
	v_exp_f32_e32 v71, v71
	v_exp_f32_e32 v72, v72
	v_exp_f32_e32 v73, v73
	v_exp_f32_e32 v74, v74
	v_exp_f32_e32 v75, v75
	v_add_f32_e32 v228, v68, v69
	v_add_f32_e32 v228, v228, v70
	v_add_f32_e32 v228, v228, v71
	v_add_f32_e32 v228, v228, v72
	v_add_f32_e32 v228, v228, v73
	v_add_f32_e32 v228, v228, v74
	v_add_f32_e32 v228, v228, v75
	v_cvt_pk_bf16_f32 v68, v68, v69
	v_cvt_pk_bf16_f32 v69, v70, v71
	v_cvt_pk_bf16_f32 v70, v72, v73
	v_cvt_pk_bf16_f32 v71, v74, v75
	v_exp_f32_e32 v76, v76
	v_exp_f32_e32 v77, v77
	v_exp_f32_e32 v78, v78
	v_exp_f32_e32 v79, v79
	v_exp_f32_e32 v80, v80
	v_exp_f32_e32 v81, v81
	v_exp_f32_e32 v82, v82
	v_exp_f32_e32 v83, v83
	v_add_f32_e32 v229, v76, v77
	v_add_f32_e32 v229, v229, v78
	v_add_f32_e32 v229, v229, v79
	v_add_f32_e32 v229, v229, v80
	v_add_f32_e32 v229, v229, v81
	v_add_f32_e32 v229, v229, v82
	v_add_f32_e32 v229, v229, v83
	v_cvt_pk_bf16_f32 v76, v76, v77
	v_cvt_pk_bf16_f32 v77, v78, v79
	v_cvt_pk_bf16_f32 v78, v80, v81
	v_cvt_pk_bf16_f32 v79, v82, v83
	v_exp_f32_e32 v84, v84
	v_exp_f32_e32 v85, v85
	s_waitcnt lgkmcnt(11)
	v_mfma_f32_16x16x32_bf16 v[4:7], v[180:183], v[68:71], v[4:7]
	v_exp_f32_e32 v86, v86
	v_exp_f32_e32 v87, v87
	s_waitcnt lgkmcnt(10)
	v_mfma_f32_16x16x32_bf16 v[12:15], v[184:187], v[68:71], v[12:15]
	v_exp_f32_e32 v88, v88
	v_exp_f32_e32 v89, v89
	s_waitcnt lgkmcnt(9)
	v_mfma_f32_16x16x32_bf16 v[20:23], v[188:191], v[68:71], v[20:23]
	v_exp_f32_e32 v90, v90
	v_exp_f32_e32 v91, v91
	s_waitcnt lgkmcnt(8)
	v_mfma_f32_16x16x32_bf16 v[28:31], v[192:195], v[68:71], v[28:31]
	v_add_f32_e32 v228, v228, v84
	v_add_f32_e32 v228, v228, v85
	v_add_f32_e32 v228, v228, v86
	v_add_f32_e32 v228, v228, v87
	s_waitcnt lgkmcnt(7)
	v_mfma_f32_16x16x32_bf16 v[36:39], v[148:151], v[68:71], v[36:39]
	v_add_f32_e32 v228, v228, v88
	v_add_f32_e32 v228, v228, v89
	v_add_f32_e32 v228, v228, v90
	v_add_f32_e32 v228, v228, v91
	s_waitcnt lgkmcnt(6)
	v_mfma_f32_16x16x32_bf16 v[44:47], v[152:155], v[68:71], v[44:47]
	v_cvt_pk_bf16_f32 v84, v84, v85
	v_cvt_pk_bf16_f32 v85, v86, v87
	v_cvt_pk_bf16_f32 v86, v88, v89
	v_cvt_pk_bf16_f32 v87, v90, v91
	s_waitcnt lgkmcnt(5)
	v_mfma_f32_16x16x32_bf16 v[52:55], v[156:159], v[68:71], v[52:55]
	v_exp_f32_e32 v92, v92
	v_exp_f32_e32 v93, v93
	s_waitcnt lgkmcnt(4)
	v_mfma_f32_16x16x32_bf16 v[60:63], v[160:163], v[68:71], v[60:63]
	v_exp_f32_e32 v94, v94
	v_exp_f32_e32 v95, v95
	v_mfma_f32_16x16x32_bf16 v[8:11], v[180:183], v[76:79], v[8:11]
	v_exp_f32_e32 v96, v96
	v_exp_f32_e32 v97, v97
	ds_read_b128 v[180:183], v223 offset:16384
	v_mfma_f32_16x16x32_bf16 v[16:19], v[184:187], v[76:79], v[16:19]
	v_exp_f32_e32 v98, v98
	v_exp_f32_e32 v99, v99
	ds_read_b128 v[184:187], v223 offset:18432
	v_mfma_f32_16x16x32_bf16 v[24:27], v[188:191], v[76:79], v[24:27]
	v_add_f32_e32 v229, v229, v92
	v_add_f32_e32 v229, v229, v93
	v_add_f32_e32 v229, v229, v94
	v_add_f32_e32 v229, v229, v95
	ds_read_b128 v[188:191], v223 offset:20480
	v_mfma_f32_16x16x32_bf16 v[32:35], v[192:195], v[76:79], v[32:35]
	v_add_f32_e32 v229, v229, v96
	v_add_f32_e32 v229, v229, v97
	v_add_f32_e32 v229, v229, v98
	v_add_f32_e32 v229, v229, v99
	ds_read_b128 v[192:195], v223 offset:22528
	v_mfma_f32_16x16x32_bf16 v[40:43], v[148:151], v[76:79], v[40:43]
	v_cvt_pk_bf16_f32 v92, v92, v93
	v_cvt_pk_bf16_f32 v93, v94, v95
	v_cvt_pk_bf16_f32 v94, v96, v97
	v_cvt_pk_bf16_f32 v95, v98, v99
	v_mfma_f32_16x16x32_bf16 v[48:51], v[152:155], v[76:79], v[48:51]
	v_mfma_f32_16x16x32_bf16 v[56:59], v[156:159], v[76:79], v[56:59]
	v_mfma_f32_16x16x32_bf16 v[64:67], v[160:163], v[76:79], v[64:67]
	s_nop 1
	s_waitcnt lgkmcnt(7)
	v_mfma_f32_16x16x32_bf16 v[4:7], v[164:167], v[84:87], v[4:7]
	s_waitcnt lgkmcnt(6)
	v_mfma_f32_16x16x32_bf16 v[12:15], v[168:171], v[84:87], v[12:15]
	s_waitcnt lgkmcnt(5)
	v_mfma_f32_16x16x32_bf16 v[20:23], v[172:175], v[84:87], v[20:23]
	s_waitcnt lgkmcnt(4)
	v_mfma_f32_16x16x32_bf16 v[28:31], v[176:179], v[84:87], v[28:31]
	s_waitcnt lgkmcnt(3)
	v_mfma_f32_16x16x32_bf16 v[36:39], v[180:183], v[84:87], v[36:39]
	s_waitcnt lgkmcnt(2)
	v_mfma_f32_16x16x32_bf16 v[44:47], v[184:187], v[84:87], v[44:47]
	s_waitcnt lgkmcnt(1)
	v_mfma_f32_16x16x32_bf16 v[52:55], v[188:191], v[84:87], v[52:55]
	s_waitcnt lgkmcnt(0)
	v_mfma_f32_16x16x32_bf16 v[60:63], v[192:195], v[84:87], v[60:63]
	v_mfma_f32_16x16x32_bf16 v[8:11], v[164:167], v[92:95], v[8:11]
	v_mfma_f32_16x16x32_bf16 v[16:19], v[168:171], v[92:95], v[16:19]
	v_mfma_f32_16x16x32_bf16 v[24:27], v[172:175], v[92:95], v[24:27]
	v_mfma_f32_16x16x32_bf16 v[32:35], v[176:179], v[92:95], v[32:35]
	v_mfma_f32_16x16x32_bf16 v[40:43], v[180:183], v[92:95], v[40:43]
	v_mfma_f32_16x16x32_bf16 v[48:51], v[184:187], v[92:95], v[48:51]
	v_mfma_f32_16x16x32_bf16 v[56:59], v[188:191], v[92:95], v[56:59]
	v_mfma_f32_16x16x32_bf16 v[64:67], v[192:195], v[92:95], v[64:67]
	v_add_f32_e32 v126, v126, v228
	v_add_f32_e32 v127, v127, v229
	s_sub_u32 s48, s48, 1
	s_cmp_lg_u32 s48, 0
	s_cbranch_scc1 .Latt16_loop
	s_waitcnt vmcnt(0)
	s_barrier
	ds_read_b128 v[148:151], v222 offset:24576
	ds_read_b128 v[152:155], v222 offset:26624
	ds_read_b128 v[156:159], v222 offset:28672
	ds_read_b128 v[160:163], v222 offset:30720
	ds_read_b128 v[164:167], v223 offset:24576
	ds_read_b128 v[168:171], v223 offset:26624
	ds_read_b128 v[172:175], v223 offset:28672
	ds_read_b128 v[176:179], v223 offset:30720
	ds_read_b128 v[180:183], v222 offset:32768
	ds_read_b128 v[184:187], v222 offset:34816
	ds_read_b128 v[188:191], v222 offset:36864
	ds_read_b128 v[192:195], v222 offset:38912
	s_waitcnt lgkmcnt(11)
	v_mfma_f32_16x16x32_bf16 v[68:71], v[148:151], v[100:103], v[116:119]
	s_waitcnt lgkmcnt(10)
	v_mfma_f32_16x16x32_bf16 v[72:75], v[152:155], v[100:103], v[116:119]
	s_waitcnt lgkmcnt(9)
	v_mfma_f32_16x16x32_bf16 v[84:87], v[156:159], v[100:103], v[116:119]
	s_waitcnt lgkmcnt(8)
	v_mfma_f32_16x16x32_bf16 v[88:91], v[160:163], v[100:103], v[116:119]
	v_mfma_f32_16x16x32_bf16 v[76:79], v[148:151], v[108:111], v[120:123]
	ds_read_b128 v[148:151], v222 offset:40960
	v_mfma_f32_16x16x32_bf16 v[80:83], v[152:155], v[108:111], v[120:123]
	ds_read_b128 v[152:155], v222 offset:43008
	v_mfma_f32_16x16x32_bf16 v[92:95], v[156:159], v[108:111], v[120:123]
	ds_read_b128 v[156:159], v222 offset:45056
	v_mfma_f32_16x16x32_bf16 v[96:99], v[160:163], v[108:111], v[120:123]
	ds_read_b128 v[160:163], v222 offset:47104
	s_waitcnt lgkmcnt(11)
	v_mfma_f32_16x16x32_bf16 v[68:71], v[164:167], v[104:107], v[68:71]
	s_waitcnt lgkmcnt(10)
	v_mfma_f32_16x16x32_bf16 v[72:75], v[168:171], v[104:107], v[72:75]
	s_waitcnt lgkmcnt(9)
	v_mfma_f32_16x16x32_bf16 v[84:87], v[172:175], v[104:107], v[84:87]
	s_waitcnt lgkmcnt(8)
	v_mfma_f32_16x16x32_bf16 v[88:91], v[176:179], v[104:107], v[88:91]
	v_mfma_f32_16x16x32_bf16 v[76:79], v[164:167], v[112:115], v[76:79]
	ds_read_b128 v[164:167], v223 offset:32768
	v_mfma_f32_16x16x32_bf16 v[80:83], v[168:171], v[112:115], v[80:83]
	ds_read_b128 v[168:171], v223 offset:34816
	v_mfma_f32_16x16x32_bf16 v[92:95], v[172:175], v[112:115], v[92:95]
	ds_read_b128 v[172:175], v223 offset:36864
	v_mfma_f32_16x16x32_bf16 v[96:99], v[176:179], v[112:115], v[96:99]
	ds_read_b128 v[176:179], v223 offset:38912
	s_nop 7
	v_max3_f32 v200, v68, v69, v70
	v_max3_f32 v201, v71, v72, v73
	v_max3_f32 v202, v74, v75, v84
	v_max3_f32 v203, v85, v86, v87
	v_max3_f32 v204, v88, v89, v90
	v_max3_f32 v200, v200, v201, v91
	v_max3_f32 v202, v202, v203, v204
	v_max_f32_e32 v196, v200, v202
	v_max3_f32 v205, v76, v77, v78
	v_max3_f32 v206, v79, v80, v81
	v_max3_f32 v207, v82, v83, v92
	v_max3_f32 v208, v93, v94, v95
	v_max3_f32 v209, v96, v97, v98
	v_max3_f32 v205, v205, v206, v99
	v_max3_f32 v207, v207, v208, v209
	v_max_f32_e32 v197, v205, v207
	v_max_f32_e32 v198, v196, v197
	v_cmp_lt_f32_e32 vcc, 0x41000000, v198
	s_cbranch_vccnz .Latt16_resc_l
.Latt16_cont_l:
	v_exp_f32_e32 v68, v68
	v_exp_f32_e32 v69, v69
	v_exp_f32_e32 v70, v70
	v_exp_f32_e32 v71, v71
	v_exp_f32_e32 v72, v72
	v_exp_f32_e32 v73, v73
	v_exp_f32_e32 v74, v74
	v_exp_f32_e32 v75, v75
	v_add_f32_e32 v228, v68, v69
	v_add_f32_e32 v228, v228, v70
	v_add_f32_e32 v228, v228, v71
	v_add_f32_e32 v228, v228, v72
	v_add_f32_e32 v228, v228, v73
	v_add_f32_e32 v228, v228, v74
	v_add_f32_e32 v228, v228, v75
	v_cvt_pk_bf16_f32 v68, v68, v69
	v_cvt_pk_bf16_f32 v69, v70, v71
	v_cvt_pk_bf16_f32 v70, v72, v73
	v_cvt_pk_bf16_f32 v71, v74, v75
	v_exp_f32_e32 v76, v76
	v_exp_f32_e32 v77, v77
	v_exp_f32_e32 v78, v78
	v_exp_f32_e32 v79, v79
	v_exp_f32_e32 v80, v80
	v_exp_f32_e32 v81, v81
	v_exp_f32_e32 v82, v82
	v_exp_f32_e32 v83, v83
	v_add_f32_e32 v229, v76, v77
	v_add_f32_e32 v229, v229, v78
	v_add_f32_e32 v229, v229, v79
	v_add_f32_e32 v229, v229, v80
	v_add_f32_e32 v229, v229, v81
	v_add_f32_e32 v229, v229, v82
	v_add_f32_e32 v229, v229, v83
	v_cvt_pk_bf16_f32 v76, v76, v77
	v_cvt_pk_bf16_f32 v77, v78, v79
	v_cvt_pk_bf16_f32 v78, v80, v81
	v_cvt_pk_bf16_f32 v79, v82, v83
	v_exp_f32_e32 v84, v84
	v_exp_f32_e32 v85, v85
	s_waitcnt lgkmcnt(11)
	v_mfma_f32_16x16x32_bf16 v[4:7], v[180:183], v[68:71], v[4:7]
	v_exp_f32_e32 v86, v86
	v_exp_f32_e32 v87, v87
	s_waitcnt lgkmcnt(10)
	v_mfma_f32_16x16x32_bf16 v[12:15], v[184:187], v[68:71], v[12:15]
	v_exp_f32_e32 v88, v88
	v_exp_f32_e32 v89, v89
	s_waitcnt lgkmcnt(9)
	v_mfma_f32_16x16x32_bf16 v[20:23], v[188:191], v[68:71], v[20:23]
	v_exp_f32_e32 v90, v90
	v_exp_f32_e32 v91, v91
	s_waitcnt lgkmcnt(8)
	v_mfma_f32_16x16x32_bf16 v[28:31], v[192:195], v[68:71], v[28:31]
	v_add_f32_e32 v228, v228, v84
	v_add_f32_e32 v228, v228, v85
	v_add_f32_e32 v228, v228, v86
	v_add_f32_e32 v228, v228, v87
	s_waitcnt lgkmcnt(7)
	v_mfma_f32_16x16x32_bf16 v[36:39], v[148:151], v[68:71], v[36:39]
	v_add_f32_e32 v228, v228, v88
	v_add_f32_e32 v228, v228, v89
	v_add_f32_e32 v228, v228, v90
	v_add_f32_e32 v228, v228, v91
	s_waitcnt lgkmcnt(6)
	v_mfma_f32_16x16x32_bf16 v[44:47], v[152:155], v[68:71], v[44:47]
	v_cvt_pk_bf16_f32 v84, v84, v85
	v_cvt_pk_bf16_f32 v85, v86, v87
	v_cvt_pk_bf16_f32 v86, v88, v89
	v_cvt_pk_bf16_f32 v87, v90, v91
	s_waitcnt lgkmcnt(5)
	v_mfma_f32_16x16x32_bf16 v[52:55], v[156:159], v[68:71], v[52:55]
	v_exp_f32_e32 v92, v92
	v_exp_f32_e32 v93, v93
	s_waitcnt lgkmcnt(4)
	v_mfma_f32_16x16x32_bf16 v[60:63], v[160:163], v[68:71], v[60:63]
	v_exp_f32_e32 v94, v94
	v_exp_f32_e32 v95, v95
	v_mfma_f32_16x16x32_bf16 v[8:11], v[180:183], v[76:79], v[8:11]
	v_exp_f32_e32 v96, v96
	v_exp_f32_e32 v97, v97
	ds_read_b128 v[180:183], v223 offset:40960
	v_mfma_f32_16x16x32_bf16 v[16:19], v[184:187], v[76:79], v[16:19]
	v_exp_f32_e32 v98, v98
	v_exp_f32_e32 v99, v99
	ds_read_b128 v[184:187], v223 offset:43008
	v_mfma_f32_16x16x32_bf16 v[24:27], v[188:191], v[76:79], v[24:27]
	v_add_f32_e32 v229, v229, v92
	v_add_f32_e32 v229, v229, v93
	v_add_f32_e32 v229, v229, v94
	v_add_f32_e32 v229, v229, v95
	ds_read_b128 v[188:191], v223 offset:45056
	v_mfma_f32_16x16x32_bf16 v[32:35], v[192:195], v[76:79], v[32:35]
	v_add_f32_e32 v229, v229, v96
	v_add_f32_e32 v229, v229, v97
	v_add_f32_e32 v229, v229, v98
	v_add_f32_e32 v229, v229, v99
	ds_read_b128 v[192:195], v223 offset:47104
	v_mfma_f32_16x16x32_bf16 v[40:43], v[148:151], v[76:79], v[40:43]
	v_cvt_pk_bf16_f32 v92, v92, v93
	v_cvt_pk_bf16_f32 v93, v94, v95
	v_cvt_pk_bf16_f32 v94, v96, v97
	v_cvt_pk_bf16_f32 v95, v98, v99
	v_mfma_f32_16x16x32_bf16 v[48:51], v[152:155], v[76:79], v[48:51]
	v_mfma_f32_16x16x32_bf16 v[56:59], v[156:159], v[76:79], v[56:59]
	v_mfma_f32_16x16x32_bf16 v[64:67], v[160:163], v[76:79], v[64:67]
	s_nop 1
	s_waitcnt lgkmcnt(7)
	v_mfma_f32_16x16x32_bf16 v[4:7], v[164:167], v[84:87], v[4:7]
	s_waitcnt lgkmcnt(6)
	v_mfma_f32_16x16x32_bf16 v[12:15], v[168:171], v[84:87], v[12:15]
	s_waitcnt lgkmcnt(5)
	v_mfma_f32_16x16x32_bf16 v[20:23], v[172:175], v[84:87], v[20:23]
	s_waitcnt lgkmcnt(4)
	v_mfma_f32_16x16x32_bf16 v[28:31], v[176:179], v[84:87], v[28:31]
	s_waitcnt lgkmcnt(3)
	v_mfma_f32_16x16x32_bf16 v[36:39], v[180:183], v[84:87], v[36:39]
	s_waitcnt lgkmcnt(2)
	v_mfma_f32_16x16x32_bf16 v[44:47], v[184:187], v[84:87], v[44:47]
	s_waitcnt lgkmcnt(1)
	v_mfma_f32_16x16x32_bf16 v[52:55], v[188:191], v[84:87], v[52:55]
	s_waitcnt lgkmcnt(0)
	v_mfma_f32_16x16x32_bf16 v[60:63], v[192:195], v[84:87], v[60:63]
	v_mfma_f32_16x16x32_bf16 v[8:11], v[164:167], v[92:95], v[8:11]
	v_mfma_f32_16x16x32_bf16 v[16:19], v[168:171], v[92:95], v[16:19]
	v_mfma_f32_16x16x32_bf16 v[24:27], v[172:175], v[92:95], v[24:27]
	v_mfma_f32_16x16x32_bf16 v[32:35], v[176:179], v[92:95], v[32:35]
	v_mfma_f32_16x16x32_bf16 v[40:43], v[180:183], v[92:95], v[40:43]
	v_mfma_f32_16x16x32_bf16 v[48:51], v[184:187], v[92:95], v[48:51]
	v_mfma_f32_16x16x32_bf16 v[56:59], v[188:191], v[92:95], v[56:59]
	v_mfma_f32_16x16x32_bf16 v[64:67], v[192:195], v[92:95], v[64:67]
	v_add_f32_e32 v126, v126, v228
	v_add_f32_e32 v127, v127, v229
	ds_bpermute_b32 v199, v226, v126
	s_waitcnt lgkmcnt(0)
	v_add_f32_e32 v126, v126, v199
	ds_bpermute_b32 v199, v227, v126
	s_waitcnt lgkmcnt(0)
	v_add_f32_e32 v126, v126, v199
	ds_bpermute_b32 v199, v226, v127
	s_waitcnt lgkmcnt(0)
	v_add_f32_e32 v127, v127, v199
	ds_bpermute_b32 v199, v227, v127
	s_waitcnt lgkmcnt(0)
	v_add_f32_e32 v127, v127, v199
	s_nop 7
	v_rcp_f32_e32 v196, v126
	v_rcp_f32_e32 v197, v127
	v_lshlrev_b32_e32 v198, 3, v135
	v_lshlrev_b32_e32 v199, 4, v135
	v_sub_u32_e32 v200, v224, v199
	v_add_u32_e32 v200, v200, v198
	v_sub_u32_e32 v201, v225, v199
	v_add_u32_e32 v201, v201, v198
	v_mul_f32_e32 v4, v4, v196
	v_mul_f32_e32 v5, v5, v196
	v_mul_f32_e32 v6, v6, v196
	v_mul_f32_e32 v7, v7, v196
	v_cvt_pk_bf16_f32 v4, v4, v5
	v_cvt_pk_bf16_f32 v5, v6, v7
	global_store_dwordx2 v200, v[4:5], s[50:51]
	v_mul_f32_e32 v8, v8, v197
	v_mul_f32_e32 v9, v9, v197
	v_mul_f32_e32 v10, v10, v197
	v_mul_f32_e32 v11, v11, v197
	v_cvt_pk_bf16_f32 v8, v8, v9
	v_cvt_pk_bf16_f32 v9, v10, v11
	global_store_dwordx2 v201, v[8:9], s[50:51]
	v_mul_f32_e32 v12, v12, v196
	v_mul_f32_e32 v13, v13, v196
	v_mul_f32_e32 v14, v14, v196
	v_mul_f32_e32 v15, v15, v196
	v_cvt_pk_bf16_f32 v12, v12, v13
	v_cvt_pk_bf16_f32 v13, v14, v15
	global_store_dwordx2 v200, v[12:13], s[50:51] offset:32
	v_mul_f32_e32 v16, v16, v197
	v_mul_f32_e32 v17, v17, v197
	v_mul_f32_e32 v18, v18, v197
	v_mul_f32_e32 v19, v19, v197
	v_cvt_pk_bf16_f32 v16, v16, v17
	v_cvt_pk_bf16_f32 v17, v18, v19
	global_store_dwordx2 v201, v[16:17], s[50:51] offset:32
	v_mul_f32_e32 v20, v20, v196
	v_mul_f32_e32 v21, v21, v196
	v_mul_f32_e32 v22, v22, v196
	v_mul_f32_e32 v23, v23, v196
	v_cvt_pk_bf16_f32 v20, v20, v21
	v_cvt_pk_bf16_f32 v21, v22, v23
	global_store_dwordx2 v200, v[20:21], s[50:51] offset:64
	v_mul_f32_e32 v24, v24, v197
	v_mul_f32_e32 v25, v25, v197
	v_mul_f32_e32 v26, v26, v197
	v_mul_f32_e32 v27, v27, v197
	v_cvt_pk_bf16_f32 v24, v24, v25
	v_cvt_pk_bf16_f32 v25, v26, v27
	global_store_dwordx2 v201, v[24:25], s[50:51] offset:64
	v_mul_f32_e32 v28, v28, v196
	v_mul_f32_e32 v29, v29, v196
	v_mul_f32_e32 v30, v30, v196
	v_mul_f32_e32 v31, v31, v196
	v_cvt_pk_bf16_f32 v28, v28, v29
	v_cvt_pk_bf16_f32 v29, v30, v31
	global_store_dwordx2 v200, v[28:29], s[50:51] offset:96
	v_mul_f32_e32 v32, v32, v197
	v_mul_f32_e32 v33, v33, v197
	v_mul_f32_e32 v34, v34, v197
	v_mul_f32_e32 v35, v35, v197
	v_cvt_pk_bf16_f32 v32, v32, v33
	v_cvt_pk_bf16_f32 v33, v34, v35
	global_store_dwordx2 v201, v[32:33], s[50:51] offset:96
	v_mul_f32_e32 v36, v36, v196
	v_mul_f32_e32 v37, v37, v196
	v_mul_f32_e32 v38, v38, v196
	v_mul_f32_e32 v39, v39, v196
	v_cvt_pk_bf16_f32 v36, v36, v37
	v_cvt_pk_bf16_f32 v37, v38, v39
	global_store_dwordx2 v200, v[36:37], s[50:51] offset:128
	v_mul_f32_e32 v40, v40, v197
	v_mul_f32_e32 v41, v41, v197
	v_mul_f32_e32 v42, v42, v197
	v_mul_f32_e32 v43, v43, v197
	v_cvt_pk_bf16_f32 v40, v40, v41
	v_cvt_pk_bf16_f32 v41, v42, v43
	global_store_dwordx2 v201, v[40:41], s[50:51] offset:128
	v_mul_f32_e32 v44, v44, v196
	v_mul_f32_e32 v45, v45, v196
	v_mul_f32_e32 v46, v46, v196
	v_mul_f32_e32 v47, v47, v196
	v_cvt_pk_bf16_f32 v44, v44, v45
	v_cvt_pk_bf16_f32 v45, v46, v47
	global_store_dwordx2 v200, v[44:45], s[50:51] offset:160
	v_mul_f32_e32 v48, v48, v197
	v_mul_f32_e32 v49, v49, v197
	v_mul_f32_e32 v50, v50, v197
	v_mul_f32_e32 v51, v51, v197
	v_cvt_pk_bf16_f32 v48, v48, v49
	v_cvt_pk_bf16_f32 v49, v50, v51
	global_store_dwordx2 v201, v[48:49], s[50:51] offset:160
	v_mul_f32_e32 v52, v52, v196
	v_mul_f32_e32 v53, v53, v196
	v_mul_f32_e32 v54, v54, v196
	v_mul_f32_e32 v55, v55, v196
	v_cvt_pk_bf16_f32 v52, v52, v53
	v_cvt_pk_bf16_f32 v53, v54, v55
	global_store_dwordx2 v200, v[52:53], s[50:51] offset:192
	v_mul_f32_e32 v56, v56, v197
	v_mul_f32_e32 v57, v57, v197
	v_mul_f32_e32 v58, v58, v197
	v_mul_f32_e32 v59, v59, v197
	v_cvt_pk_bf16_f32 v56, v56, v57
	v_cvt_pk_bf16_f32 v57, v58, v59
	global_store_dwordx2 v201, v[56:57], s[50:51] offset:192
	v_mul_f32_e32 v60, v60, v196
	v_mul_f32_e32 v61, v61, v196
	v_mul_f32_e32 v62, v62, v196
	v_mul_f32_e32 v63, v63, v196
	v_cvt_pk_bf16_f32 v60, v60, v61
	v_cvt_pk_bf16_f32 v61, v62, v63
	global_store_dwordx2 v200, v[60:61], s[50:51] offset:224
	v_mul_f32_e32 v64, v64, v197
	v_mul_f32_e32 v65, v65, v197
	v_mul_f32_e32 v66, v66, v197
	v_mul_f32_e32 v67, v67, v197
	v_cvt_pk_bf16_f32 v64, v64, v65
	v_cvt_pk_bf16_f32 v65, v66, v67
	global_store_dwordx2 v201, v[64:65], s[50:51] offset:224
	s_add_u32 s55, s55, 1
	s_add_u32 s40, s40, s41
	s_cmpk_lt_u32 s40, 0x600
	s_cbranch_scc1 .Latt16_item
	s_branch .Latt16_done
